# gMLP items: up-front loads + LayerNorm butterfly reductions via DPP (quad_perm/row_half_mirror/row_mirror) instead of ds_bpermute
# baseline (speedup 1.0000x reference)
.LBB0_1177:
	v_mov_b32_e32 v0, v218
	s_or_b32 s30, s8, s44
	v_readfirstlane_b32 s28, v0
	s_ashr_i32 s8, s28, 2
	s_and_b32 s31, s8, -16
	v_bfe_u32 v66, v0, 4, 2
	s_add_i32 s8, s31, s30
	v_and_b32_e32 v88, 63, v0
	v_and_b32_e32 v89, 15, v0
	v_or_b32_e32 v2, s8, v66
	v_mov_b64_e32 v[0:1], s[42:43]
	v_mad_i64_i32 v[0:1], s[8:9], v2, s70, v[0:1]
	v_lshlrev_b32_e32 v32, 4, v89
	v_lshl_add_u64 v[0:1], v[0:1], 0, v[32:33]
	s_mov_b64 s[8:9], 0x400
	v_lshl_add_u64 v[6:7], v[0:1], 0, s[8:9]
	global_load_dwordx4 v[8:11], v[0:1], off offset:1024
	global_load_dwordx4 v[12:15], v[0:1], off offset:1280
	global_load_dwordx4 v[16:19], v[0:1], off offset:1536
	s_nop 0
	global_load_dwordx4 v[0:3], v[0:1], off offset:1792
	v_add_co_u32_e32 v116, vcc, 0x15000, v6
	s_nop 1
	v_addc_co_u32_e32 v117, vcc, 0, v7, vcc
	global_load_dwordx4 v[62:65], v[116:117], off
	global_load_dwordx4 v[58:61], v[116:117], off offset:256
	global_load_dwordx4 v[54:57], v[116:117], off offset:512
	global_load_dwordx4 v[50:53], v[116:117], off offset:768
	v_add_co_u32_e32 v116, vcc, 0x2a000, v6
	s_nop 1
	v_addc_co_u32_e32 v117, vcc, 0, v7, vcc
	global_load_dwordx4 v[46:49], v[116:117], off
	global_load_dwordx4 v[42:45], v[116:117], off offset:256
	global_load_dwordx4 v[38:41], v[116:117], off offset:512
	global_load_dwordx4 v[34:37], v[116:117], off offset:768
	v_add_co_u32_e32 v116, vcc, 0x3f000, v6
	s_nop 1
	v_addc_co_u32_e32 v117, vcc, 0, v7, vcc
	global_load_dwordx4 v[28:31], v[116:117], off
	global_load_dwordx4 v[24:27], v[116:117], off offset:256
	global_load_dwordx4 v[20:23], v[116:117], off offset:512
	global_load_dwordx4 v[118:121], v[116:117], off offset:768
	v_lshlrev_b32_e32 v122, 5, v89
	global_load_dwordx4 v[124:127], v122, s[14:15] offset:16
	global_load_dwordx4 v[128:131], v122, s[14:15]
	global_load_dwordx4 v[132:135], v122, s[16:17] offset:16
	global_load_dwordx4 v[136:139], v122, s[16:17]
	v_readlane_b32 s60, v252, 50
	v_readlane_b32 s61, v252, 51
	v_or_b32_e32 v158, s31, v89
	v_lshlrev_b32_e32 v159, 8, v158
	v_lshl_add_u32 v159, v66, 4, v159
	v_add_u32_e32 v160, s30, v158
	v_mul_lo_u32 v160, v160, s70
	v_lshl_add_u32 v160, v66, 3, v160
	v_add_u32_e32 v161, s2, v158
	v_lshlrev_b32_e32 v161, 2, v161
	global_load_dwordx4 v[140:143], v159, s[18:19]
	global_load_dwordx4 v[144:147], v159, s[18:19] offset:64
	global_load_dwordx4 v[148:151], v159, s[18:19] offset:128
	global_load_dwordx4 v[152:155], v159, s[18:19] offset:192
	global_load_dwordx2 v[164:165], v160, s[34:35]
	global_load_dwordx2 v[166:167], v160, s[34:35] offset:2048
	global_load_dwordx2 v[168:169], v160, s[34:35] offset:32
	global_load_dwordx2 v[170:171], v160, s[34:35] offset:2080
	global_load_dwordx2 v[172:173], v160, s[34:35] offset:64
	global_load_dwordx2 v[174:175], v160, s[34:35] offset:2112
	global_load_dwordx2 v[176:177], v160, s[34:35] offset:96
	global_load_dwordx2 v[178:179], v160, s[34:35] offset:2144
	global_load_dwordx2 v[180:181], v160, s[34:35] offset:128
	global_load_dwordx2 v[182:183], v160, s[34:35] offset:2176
	global_load_dwordx2 v[184:185], v160, s[34:35] offset:160
	global_load_dwordx2 v[186:187], v160, s[34:35] offset:2208
	global_load_dwordx2 v[188:189], v160, s[34:35] offset:192
	global_load_dwordx2 v[190:191], v160, s[34:35] offset:2240
	global_load_dwordx2 v[192:193], v160, s[34:35] offset:224
	global_load_dwordx2 v[194:195], v160, s[34:35] offset:2272
	global_load_dword v156, v161, s[60:61]
	v_and_b32_e32 v5, 64, v226
	v_add_u32_e32 v162, 64, v5
	v_lshlrev_b32_e32 v4, 3, v89
	s_xor_b64 s[20:21], s[10:11], -1
	s_cmp_lt_i32 s65, 2
	s_mov_b64 s[10:11], -1
	s_waitcnt vmcnt(40)
	v_lshlrev_b32_e32 v70, 16, v8
	v_and_b32_e32 v71, 0xffff0000, v8
	v_lshlrev_b32_e32 v72, 16, v9
	v_and_b32_e32 v73, 0xffff0000, v9
	v_lshlrev_b32_e32 v74, 16, v10
	v_and_b32_e32 v75, 0xffff0000, v10
	v_lshlrev_b32_e32 v76, 16, v11
	v_and_b32_e32 v77, 0xffff0000, v11
	v_add_f32_e32 v5, v70, v71
	v_add_f32_e32 v8, v72, v73
	v_add_f32_e32 v5, v5, v8
	v_add_f32_e32 v8, v74, v75
	v_add_f32_e32 v9, v76, v77
	v_add_f32_e32 v8, v8, v9
	v_add_f32_e32 v5, v5, v8
	v_mul_f32_e32 v8, v71, v71
	v_mul_f32_e32 v9, v73, v73
	v_fmac_f32_e32 v8, v70, v70
	v_fmac_f32_e32 v9, v72, v72
	v_add_f32_e32 v8, v8, v9
	v_mul_f32_e32 v9, v75, v75
	v_mul_f32_e32 v10, v77, v77
	v_fmac_f32_e32 v9, v74, v74
	v_fmac_f32_e32 v10, v76, v76
	v_add_f32_e32 v9, v9, v10
	s_waitcnt vmcnt(39)
	v_lshlrev_b32_e32 v78, 16, v12
	v_and_b32_e32 v79, 0xffff0000, v12
	v_lshlrev_b32_e32 v80, 16, v13
	v_and_b32_e32 v81, 0xffff0000, v13
	v_add_f32_e32 v8, v8, v9
	v_lshlrev_b32_e32 v82, 16, v14
	v_and_b32_e32 v83, 0xffff0000, v14
	v_lshlrev_b32_e32 v84, 16, v15
	v_and_b32_e32 v85, 0xffff0000, v15
	v_add_f32_e32 v9, v78, v79
	v_add_f32_e32 v10, v80, v81
	v_add_f32_e32 v9, v9, v10
	v_add_f32_e32 v10, v82, v83
	v_add_f32_e32 v11, v84, v85
	v_add_f32_e32 v10, v10, v11
	v_add_f32_e32 v5, 0, v5
	v_add_f32_e32 v9, v9, v10
	v_add_f32_e32 v5, v5, v9
	v_mul_f32_e32 v9, v79, v79
	v_mul_f32_e32 v10, v81, v81
	s_waitcnt vmcnt(37)
	v_lshlrev_b32_e32 v103, 16, v0
	v_and_b32_e32 v102, 0xffff0000, v0
	v_lshlrev_b32_e32 v101, 16, v1
	v_and_b32_e32 v100, 0xffff0000, v1
	v_fmac_f32_e32 v9, v78, v78
	v_fmac_f32_e32 v10, v80, v80
	v_lshlrev_b32_e32 v99, 16, v2
	v_and_b32_e32 v98, 0xffff0000, v2
	v_lshlrev_b32_e32 v97, 16, v3
	v_and_b32_e32 v96, 0xffff0000, v3
	v_add_f32_e32 v0, v103, v102
	v_add_f32_e32 v1, v101, v100
	v_add_f32_e32 v9, v9, v10
	v_mul_f32_e32 v10, v83, v83
	v_mul_f32_e32 v11, v85, v85
	v_add_f32_e32 v0, v0, v1
	v_add_f32_e32 v1, v99, v98
	v_add_f32_e32 v2, v97, v96
	v_fmac_f32_e32 v10, v82, v82
	v_fmac_f32_e32 v11, v84, v84
	v_add_f32_e32 v1, v1, v2
	v_add_f32_e32 v10, v10, v11
	v_add_f32_e32 v0, v0, v1
	v_mul_f32_e32 v1, v102, v102
	v_mul_f32_e32 v2, v100, v100
	v_add_f32_e32 v9, v9, v10
	v_lshlrev_b32_e32 v86, 16, v16
	v_and_b32_e32 v87, 0xffff0000, v16
	v_lshlrev_b32_e32 v90, 16, v17
	v_and_b32_e32 v91, 0xffff0000, v17
	v_fmac_f32_e32 v1, v103, v103
	v_fmac_f32_e32 v2, v101, v101
	v_add_f32_e32 v8, v8, v9
	v_lshlrev_b32_e32 v92, 16, v18
	v_and_b32_e32 v93, 0xffff0000, v18
	v_lshlrev_b32_e32 v94, 16, v19
	v_and_b32_e32 v95, 0xffff0000, v19
	v_add_f32_e32 v9, v86, v87
	v_add_f32_e32 v10, v90, v91
	v_add_f32_e32 v1, v1, v2
	v_mul_f32_e32 v2, v98, v98
	v_mul_f32_e32 v3, v96, v96
	v_add_f32_e32 v9, v9, v10
	v_add_f32_e32 v10, v92, v93
	v_add_f32_e32 v11, v94, v95
	v_fmac_f32_e32 v2, v99, v99
	v_fmac_f32_e32 v3, v97, v97
	v_add_f32_e32 v10, v10, v11
	v_add_f32_e32 v2, v2, v3
	v_add_f32_e32 v9, v9, v10
	v_add_f32_e32 v1, v1, v2
	v_xor_b32_e32 v2, 1, v226
	v_add_f32_e32 v5, v5, v9
	v_mul_f32_e32 v9, v87, v87
	v_mul_f32_e32 v10, v91, v91
	v_cmp_lt_i32_e32 vcc, v2, v162
	v_fmac_f32_e32 v9, v86, v86
	v_fmac_f32_e32 v10, v90, v90
	v_cndmask_b32_e32 v2, v226, v2, vcc
	v_add_f32_e32 v9, v9, v10
	v_mul_f32_e32 v10, v93, v93
	v_mul_f32_e32 v11, v95, v95
	v_add_f32_e32 v0, v5, v0
	v_lshlrev_b32_e32 v69, 2, v2
	v_fmac_f32_e32 v10, v92, v92
	v_fmac_f32_e32 v11, v94, v94
	s_nop 1
	v_mov_b32_dpp v2, v0 quad_perm:[1,0,3,2] row_mask:0xf bank_mask:0xf
	v_add_f32_e32 v10, v10, v11
	v_add_f32_e32 v9, v9, v10
	v_add_f32_e32 v8, v8, v9
	v_add_f32_e32 v1, v8, v1
	s_waitcnt lgkmcnt(0)
	v_add_f32_e32 v0, v0, v2
	s_nop 1
	v_mov_b32_dpp v2, v1 quad_perm:[1,0,3,2] row_mask:0xf bank_mask:0xf
	v_lshlrev_b32_e32 v12, 2, v4
	s_waitcnt lgkmcnt(0)
	v_add_f32_e32 v1, v1, v2
	v_xor_b32_e32 v2, 2, v226
	v_cmp_lt_i32_e32 vcc, v2, v162
	s_nop 1
	v_cndmask_b32_e32 v2, v226, v2, vcc
	v_lshlrev_b32_e32 v68, 2, v2
	s_nop 1
	v_mov_b32_dpp v2, v0 quad_perm:[2,3,0,1] row_mask:0xf bank_mask:0xf
	s_waitcnt lgkmcnt(0)
	v_add_f32_e32 v0, v0, v2
	s_nop 1
	v_mov_b32_dpp v2, v1 quad_perm:[2,3,0,1] row_mask:0xf bank_mask:0xf
	s_waitcnt lgkmcnt(0)
	v_add_f32_e32 v1, v1, v2
	v_xor_b32_e32 v2, 4, v226
	v_cmp_lt_i32_e32 vcc, v2, v162
	s_nop 1
	v_cndmask_b32_e32 v2, v226, v2, vcc
	v_lshlrev_b32_e32 v67, 2, v2
	s_nop 1
	v_mov_b32_dpp v2, v0 row_half_mirror row_mask:0xf bank_mask:0xf
	s_waitcnt lgkmcnt(0)
	v_add_f32_e32 v104, v0, v2
	s_nop 1
	v_mov_b32_dpp v0, v1 row_half_mirror row_mask:0xf bank_mask:0xf
	s_waitcnt lgkmcnt(0)
	v_add_f32_e32 v105, v1, v0
	v_xor_b32_e32 v0, 8, v226
	v_cmp_lt_i32_e32 vcc, v0, v162
	s_nop 1
	v_cndmask_b32_e32 v0, v226, v0, vcc
	v_lshlrev_b32_e32 v32, 2, v0
	v_add_co_u32_e32 v0, vcc, 0x15000, v6
	s_nop 1
	v_mov_b32_dpp v106, v104 row_mirror row_mask:0xf bank_mask:0xf
	s_nop 0
	v_addc_co_u32_e32 v1, vcc, 0, v7, vcc
	v_add_co_u32_e32 v0, vcc, 0x2a000, v6
	s_nop 1
	v_mov_b32_dpp v107, v105 row_mirror row_mask:0xf bank_mask:0xf
	s_nop 0
	v_addc_co_u32_e32 v1, vcc, 0, v7, vcc
	v_add_co_u32_e32 v0, vcc, 0x3f000, v6
	s_nop 1
	v_addc_co_u32_e32 v1, vcc, 0, v7, vcc
	s_nop 0
	s_nop 0
	s_cbranch_scc1 .LBB0_1183
	s_cmp_gt_i32 s65, 2
	s_cbranch_scc0 .LBB0_1180
	s_mov_b64 s[10:11], 0

.LBB0_1187:
	s_waitcnt lgkmcnt(1)
	v_add_f32_e32 v75, v104, v106
	v_mul_f32_e32 v73, 0x3b000000, v75
	s_waitcnt lgkmcnt(0)
	v_add_f32_e32 v72, v105, v107
	v_mul_f32_e32 v73, v73, v73
	v_fma_f32 v72, v72, s73, -v73
	v_max_f32_e32 v72, 0, v72
	v_add_f32_e32 v72, 0x358637bd, v72
	v_cmp_gt_f32_e32 vcc, s5, v72
	v_mul_f32_e32 v73, 0x4f800000, v72
	v_fmac_f32_e32 v103, 0xbb000000, v75
	v_cndmask_b32_e32 v72, v72, v73, vcc
	v_sqrt_f32_e32 v73, v72
	v_fmac_f32_e32 v102, 0xbb000000, v75
	v_fmac_f32_e32 v101, 0xbb000000, v75
	v_fmac_f32_e32 v100, 0xbb000000, v75
	v_add_u32_e32 v74, -1, v73
	v_fma_f32 v76, -v74, v73, v72
	v_cmp_ge_f32_e64 s[10:11], 0, v76
	v_add_u32_e32 v76, 1, v73
	v_fmac_f32_e32 v99, 0xbb000000, v75
	v_cndmask_b32_e64 v74, v73, v74, s[10:11]
	v_fma_f32 v73, -v76, v73, v72
	v_cmp_lt_f32_e64 s[10:11], 0, v73
	v_fmac_f32_e32 v98, 0xbb000000, v75
	v_or_b32_e32 v70, s31, v66
	v_cndmask_b32_e64 v73, v74, v76, s[10:11]
	v_mul_f32_e32 v74, 0x37800000, v73
	v_cndmask_b32_e32 v73, v73, v74, vcc
	v_cmp_class_f32_e32 vcc, v72, v220
	v_fmac_f32_e32 v96, 0xbb000000, v75
	v_lshl_add_u32 v71, v89, 4, 0
	v_cndmask_b32_e32 v72, v73, v72, vcc
	v_div_scale_f32 v73, s[8:9], v72, v72, 1.0
	v_rcp_f32_e32 v74, v73
	s_movk_i32 s8, 0x120
	v_fmac_f32_e32 v97, 0xbb000000, v75
	v_mul_lo_u32 v70, v70, s8
	v_fma_f32 v76, -v73, v74, 1.0
	v_fmac_f32_e32 v74, v76, v74
	v_div_scale_f32 v76, vcc, 1.0, v72, 1.0
	v_mul_f32_e32 v77, v76, v74
	v_fma_f32 v78, -v73, v77, v76
	v_fmac_f32_e32 v77, v78, v74
	v_fma_f32 v73, -v73, v77, v76
	v_div_fmas_f32 v73, v73, v74, v77
	v_div_fixup_f32 v76, v73, v72, 1.0
	v_mul_f32_e32 v72, v76, v103
	v_mul_f32_e32 v73, v76, v102
	s_waitcnt vmcnt(21)
	v_mov_b64_e32 v[16:17], v[118:119]
	v_mov_b64_e32 v[18:19], v[120:121]
	v_mov_b64_e32 v[0:1], v[124:125]
	v_mov_b64_e32 v[2:3], v[126:127]
	v_mov_b64_e32 v[8:9], v[128:129]
	v_mov_b64_e32 v[10:11], v[130:131]
	v_mov_b64_e32 v[4:5], v[132:133]
	v_mov_b64_e32 v[6:7], v[134:135]
	v_mov_b64_e32 v[12:13], v[136:137]
	v_mov_b64_e32 v[14:15], v[138:139]
	v_fma_f32 v72, v8, v72, v12
	v_fma_f32 v73, v9, v73, v13
	v_cvt_pk_bf16_f32 v72, v72, v73
	v_mul_f32_e32 v73, v76, v101
	v_mul_f32_e32 v74, v76, v100
	v_fma_f32 v73, v10, v73, v14
	v_fma_f32 v74, v11, v74, v15
	v_cvt_pk_bf16_f32 v73, v73, v74
	v_mul_f32_e32 v74, v76, v99
	v_mul_f32_e32 v77, v76, v98
	v_fma_f32 v74, v0, v74, v4
	v_fma_f32 v77, v1, v77, v5
	v_mul_f32_e32 v75, v76, v96
	v_cvt_pk_bf16_f32 v74, v74, v77
	v_mul_f32_e32 v77, v76, v97
	v_fma_f32 v75, v3, v75, v7
	v_add_u32_e32 v70, v71, v70
	v_fma_f32 v77, v2, v77, v6
	v_cvt_pk_bf16_f32 v75, v77, v75
	ds_write_b128 v70, v[72:75]
	v_lshlrev_b32_e32 v71, 16, v62
	v_and_b32_e32 v62, 0xffff0000, v62
	v_lshlrev_b32_e32 v72, 16, v63
	v_and_b32_e32 v63, 0xffff0000, v63
	v_lshlrev_b32_e32 v73, 16, v64
	v_and_b32_e32 v64, 0xffff0000, v64
	v_lshlrev_b32_e32 v74, 16, v65
	v_and_b32_e32 v65, 0xffff0000, v65
	v_add_f32_e32 v75, v71, v62
	v_add_f32_e32 v76, v72, v63
	v_add_f32_e32 v75, v75, v76
	v_add_f32_e32 v76, v73, v64
	v_add_f32_e32 v77, v74, v65
	v_add_f32_e32 v76, v76, v77
	v_add_f32_e32 v75, v75, v76
	v_add_f32_e32 v79, 0, v75
	v_mul_f32_e32 v75, v62, v62
	v_mul_f32_e32 v76, v63, v63
	v_fmac_f32_e32 v75, v71, v71
	v_fmac_f32_e32 v76, v72, v72
	v_add_f32_e32 v75, v75, v76
	v_mul_f32_e32 v76, v64, v64
	v_mul_f32_e32 v77, v65, v65
	v_fmac_f32_e32 v76, v73, v73
	v_fmac_f32_e32 v77, v74, v74
	v_add_f32_e32 v76, v76, v77
	v_add_f32_e32 v80, v75, v76
	v_lshlrev_b32_e32 v75, 16, v58
	v_and_b32_e32 v58, 0xffff0000, v58
	v_lshlrev_b32_e32 v76, 16, v59
	v_and_b32_e32 v59, 0xffff0000, v59
	v_lshlrev_b32_e32 v77, 16, v60
	v_and_b32_e32 v60, 0xffff0000, v60
	v_lshlrev_b32_e32 v78, 16, v61
	v_and_b32_e32 v61, 0xffff0000, v61
	v_add_f32_e32 v81, v75, v58
	v_add_f32_e32 v82, v76, v59
	v_add_f32_e32 v81, v81, v82
	v_add_f32_e32 v82, v77, v60
	v_add_f32_e32 v83, v78, v61
	v_add_f32_e32 v82, v82, v83
	v_add_f32_e32 v81, v81, v82
	v_add_f32_e32 v79, v79, v81
	v_mul_f32_e32 v81, v58, v58
	v_mul_f32_e32 v82, v59, v59
	v_fmac_f32_e32 v81, v75, v75
	v_fmac_f32_e32 v82, v76, v76
	v_add_f32_e32 v81, v81, v82
	v_mul_f32_e32 v82, v60, v60
	v_mul_f32_e32 v83, v61, v61
	v_fmac_f32_e32 v82, v77, v77
	v_fmac_f32_e32 v83, v78, v78
	v_add_f32_e32 v82, v82, v83
	v_add_f32_e32 v81, v81, v82
	v_add_f32_e32 v90, v80, v81
	v_lshlrev_b32_e32 v80, 16, v54
	v_and_b32_e32 v81, 0xffff0000, v54
	v_lshlrev_b32_e32 v82, 16, v55
	v_and_b32_e32 v83, 0xffff0000, v55
	v_lshlrev_b32_e32 v84, 16, v56
	v_and_b32_e32 v85, 0xffff0000, v56
	v_lshlrev_b32_e32 v86, 16, v57
	v_and_b32_e32 v87, 0xffff0000, v57
	v_add_f32_e32 v54, v80, v81
	v_add_f32_e32 v55, v82, v83
	v_add_f32_e32 v54, v54, v55
	v_add_f32_e32 v55, v84, v85
	v_add_f32_e32 v56, v86, v87
	v_add_f32_e32 v55, v55, v56
	v_add_f32_e32 v54, v54, v55
	v_add_f32_e32 v91, v79, v54
	v_mul_f32_e32 v54, v81, v81
	v_mul_f32_e32 v55, v83, v83
	v_fmac_f32_e32 v54, v80, v80
	v_fmac_f32_e32 v55, v82, v82
	v_add_f32_e32 v54, v54, v55
	v_mul_f32_e32 v55, v85, v85
	v_mul_f32_e32 v56, v87, v87
	v_fmac_f32_e32 v55, v84, v84
	v_fmac_f32_e32 v56, v86, v86
	v_add_f32_e32 v55, v55, v56
	v_add_f32_e32 v54, v54, v55
	v_lshlrev_b32_e32 v79, 16, v50
	v_and_b32_e32 v57, 0xffff0000, v50
	v_lshlrev_b32_e32 v56, 16, v51
	v_and_b32_e32 v55, 0xffff0000, v51
	v_add_f32_e32 v90, v90, v54
	v_lshlrev_b32_e32 v54, 16, v52
	v_and_b32_e32 v52, 0xffff0000, v52
	v_lshlrev_b32_e32 v51, 16, v53
	v_and_b32_e32 v50, 0xffff0000, v53
	v_add_f32_e32 v53, v79, v57
	v_add_f32_e32 v92, v56, v55
	v_add_f32_e32 v53, v53, v92
	v_add_f32_e32 v92, v54, v52
	v_add_f32_e32 v93, v51, v50
	v_add_f32_e32 v92, v92, v93
	v_add_f32_e32 v53, v53, v92
	v_add_f32_e32 v53, v91, v53
	v_mul_f32_e32 v91, v57, v57
	v_mul_f32_e32 v92, v55, v55
	v_fmac_f32_e32 v91, v79, v79
	v_fmac_f32_e32 v92, v56, v56
	v_add_f32_e32 v91, v91, v92
	v_mul_f32_e32 v92, v52, v52
	v_mul_f32_e32 v93, v50, v50
	v_fmac_f32_e32 v92, v54, v54
	v_fmac_f32_e32 v93, v51, v51
	v_add_f32_e32 v92, v92, v93
	v_add_f32_e32 v91, v91, v92
	v_add_f32_e32 v90, v90, v91
	s_nop 1
	v_mov_b32_dpp v91, v53 quad_perm:[1,0,3,2] row_mask:0xf bank_mask:0xf
	s_cmp_lt_i32 s65, 2
	s_mov_b64 s[10:11], -1
	s_waitcnt lgkmcnt(0)
	v_add_f32_e32 v53, v53, v91
	s_nop 1
	v_mov_b32_dpp v91, v90 quad_perm:[1,0,3,2] row_mask:0xf bank_mask:0xf
	s_waitcnt lgkmcnt(0)
	v_add_f32_e32 v90, v90, v91
	s_nop 1
	v_mov_b32_dpp v91, v53 quad_perm:[2,3,0,1] row_mask:0xf bank_mask:0xf
	s_waitcnt lgkmcnt(0)
	v_add_f32_e32 v53, v53, v91
	s_nop 1
	v_mov_b32_dpp v91, v90 quad_perm:[2,3,0,1] row_mask:0xf bank_mask:0xf
	s_waitcnt lgkmcnt(0)
	v_add_f32_e32 v90, v90, v91
	s_nop 1
	v_mov_b32_dpp v91, v53 row_half_mirror row_mask:0xf bank_mask:0xf
	s_waitcnt lgkmcnt(0)
	v_add_f32_e32 v53, v53, v91
	s_nop 1
	v_mov_b32_dpp v91, v90 row_half_mirror row_mask:0xf bank_mask:0xf
	s_waitcnt lgkmcnt(0)
	v_add_f32_e32 v90, v90, v91
	s_nop 1
	v_mov_b32_dpp v91, v53 row_mirror row_mask:0xf bank_mask:0xf
	s_nop 1
	v_mov_b32_dpp v92, v90 row_mirror row_mask:0xf bank_mask:0xf
	s_cbranch_scc1 .LBB0_1191
	s_cmp_lt_i32 s65, 3
	s_cbranch_scc0 .LBB0_1190
	v_mov_b32_e32 v79, v80
	v_mov_b32_e32 v57, v81
	v_mov_b32_e32 v56, v82
	v_mov_b32_e32 v55, v83
	v_mov_b32_e32 v54, v84
	v_mov_b32_e32 v52, v85
	v_mov_b32_e32 v51, v86
	v_mov_b32_e32 v50, v87

.LBB0_1197:
	s_waitcnt lgkmcnt(1)
	v_add_f32_e32 v53, v53, v91
	v_mul_f32_e32 v59, 0x3b000000, v53
	s_waitcnt lgkmcnt(0)
	v_add_f32_e32 v58, v90, v92
	v_mul_f32_e32 v59, v59, v59
	v_fma_f32 v58, v58, s73, -v59
	v_max_f32_e32 v58, 0, v58
	v_add_f32_e32 v58, 0x358637bd, v58
	v_cmp_gt_f32_e32 vcc, s5, v58
	v_mul_f32_e32 v59, 0x4f800000, v58
	v_fmac_f32_e32 v51, 0xbb000000, v53
	v_cndmask_b32_e32 v58, v58, v59, vcc
	v_sqrt_f32_e32 v59, v58
	v_fmac_f32_e32 v50, 0xbb000000, v53
	v_fmac_f32_e32 v55, 0xbb000000, v53
	v_fmac_f32_e32 v54, 0xbb000000, v53
	v_add_u32_e32 v60, -1, v59
	v_fma_f32 v61, -v60, v59, v58
	v_cmp_ge_f32_e64 s[10:11], 0, v61
	v_add_u32_e32 v61, 1, v59
	v_fmac_f32_e32 v52, 0xbb000000, v53
	v_cndmask_b32_e64 v60, v59, v60, s[10:11]
	v_fma_f32 v59, -v61, v59, v58
	v_cmp_lt_f32_e64 s[10:11], 0, v59
	v_fmac_f32_e32 v79, 0xbb000000, v53
	v_fmac_f32_e32 v57, 0xbb000000, v53
	v_cndmask_b32_e64 v59, v60, v61, s[10:11]
	v_mul_f32_e32 v60, 0x37800000, v59
	v_cndmask_b32_e32 v59, v59, v60, vcc
	v_cmp_class_f32_e32 vcc, v58, v220
	v_fmac_f32_e32 v56, 0xbb000000, v53
	v_lshlrev_b32_e32 v53, 16, v49
	v_cndmask_b32_e32 v58, v59, v58, vcc
	v_div_scale_f32 v59, s[8:9], v58, v58, 1.0
	v_rcp_f32_e32 v60, v59
	v_and_b32_e32 v49, 0xffff0000, v49
	v_and_b32_e32 v64, 0xffff0000, v40
	v_lshlrev_b32_e32 v65, 16, v41
	v_fma_f32 v61, -v59, v60, 1.0
	v_fmac_f32_e32 v60, v61, v60
	v_div_scale_f32 v61, vcc, 1.0, v58, 1.0
	v_mul_f32_e32 v62, v61, v60
	v_fma_f32 v63, -v59, v62, v61
	v_fmac_f32_e32 v62, v63, v60
	v_fma_f32 v59, -v59, v62, v61
	v_div_fmas_f32 v59, v59, v60, v62
	v_div_fixup_f32 v61, v59, v58, 1.0
	v_mul_f32_e32 v51, v61, v51
	v_mul_f32_e32 v50, v61, v50
	v_mul_f32_e32 v55, v61, v55
	v_mul_f32_e32 v54, v61, v54
	v_mul_f32_e32 v52, v61, v52
	v_fma_f32 v51, v2, v51, v6
	v_fma_f32 v50, v3, v50, v7
	v_mul_f32_e32 v58, v61, v79
	v_mul_f32_e32 v57, v61, v57
	v_mul_f32_e32 v56, v61, v56
	v_fma_f32 v55, v11, v55, v15
	v_fma_f32 v54, v0, v54, v4
	v_fma_f32 v52, v1, v52, v5
	v_cvt_pk_bf16_f32 v61, v51, v50
	v_lshlrev_b32_e32 v50, 16, v46
	v_and_b32_e32 v46, 0xffff0000, v46
	v_lshlrev_b32_e32 v51, 16, v47
	v_and_b32_e32 v47, 0xffff0000, v47
	v_fma_f32 v56, v10, v56, v14
	v_cvt_pk_bf16_f32 v59, v56, v55
	v_cvt_pk_bf16_f32 v60, v54, v52
	v_lshlrev_b32_e32 v52, 16, v48
	v_and_b32_e32 v48, 0xffff0000, v48
	v_add_f32_e32 v54, v50, v46
	v_add_f32_e32 v55, v51, v47
	v_add_f32_e32 v54, v54, v55
	v_add_f32_e32 v55, v52, v48
	v_add_f32_e32 v56, v53, v49
	v_fma_f32 v58, v8, v58, v12
	v_add_f32_e32 v55, v55, v56
	v_fma_f32 v57, v9, v57, v13
	v_cvt_pk_bf16_f32 v58, v58, v57
	v_add_f32_e32 v54, v54, v55
	ds_write_b128 v70, v[58:61] offset:1152
	v_add_f32_e32 v58, 0, v54
	v_mul_f32_e32 v54, v46, v46
	v_mul_f32_e32 v55, v47, v47
	v_fmac_f32_e32 v54, v50, v50
	v_fmac_f32_e32 v55, v51, v51
	v_add_f32_e32 v54, v54, v55
	v_mul_f32_e32 v55, v48, v48
	v_mul_f32_e32 v56, v49, v49
	v_fmac_f32_e32 v55, v52, v52
	v_fmac_f32_e32 v56, v53, v53
	v_add_f32_e32 v55, v55, v56
	v_add_f32_e32 v59, v54, v55
	v_lshlrev_b32_e32 v54, 16, v42
	v_and_b32_e32 v42, 0xffff0000, v42
	v_lshlrev_b32_e32 v55, 16, v43
	v_and_b32_e32 v43, 0xffff0000, v43
	v_lshlrev_b32_e32 v56, 16, v44
	v_and_b32_e32 v44, 0xffff0000, v44
	v_lshlrev_b32_e32 v57, 16, v45
	v_and_b32_e32 v45, 0xffff0000, v45
	v_add_f32_e32 v60, v54, v42
	v_add_f32_e32 v61, v55, v43
	v_add_f32_e32 v60, v60, v61
	v_add_f32_e32 v61, v56, v44
	v_add_f32_e32 v62, v57, v45
	v_add_f32_e32 v61, v61, v62
	v_add_f32_e32 v60, v60, v61
	v_add_f32_e32 v58, v58, v60
	v_mul_f32_e32 v60, v42, v42
	v_mul_f32_e32 v61, v43, v43
	v_fmac_f32_e32 v60, v54, v54
	v_fmac_f32_e32 v61, v55, v55
	v_add_f32_e32 v60, v60, v61
	v_mul_f32_e32 v61, v44, v44
	v_mul_f32_e32 v62, v45, v45
	v_fmac_f32_e32 v61, v56, v56
	v_fmac_f32_e32 v62, v57, v57
	v_add_f32_e32 v61, v61, v62
	v_add_f32_e32 v60, v60, v61
	v_add_f32_e32 v72, v59, v60
	v_lshlrev_b32_e32 v59, 16, v38
	v_and_b32_e32 v60, 0xffff0000, v38
	v_lshlrev_b32_e32 v61, 16, v39
	v_and_b32_e32 v62, 0xffff0000, v39
	v_lshlrev_b32_e32 v63, 16, v40
	v_and_b32_e32 v71, 0xffff0000, v41
	v_add_f32_e32 v38, v59, v60
	v_add_f32_e32 v39, v61, v62
	v_add_f32_e32 v38, v38, v39
	v_add_f32_e32 v39, v63, v64
	v_add_f32_e32 v40, v65, v71
	v_add_f32_e32 v39, v39, v40
	v_add_f32_e32 v38, v38, v39
	v_add_f32_e32 v73, v58, v38
	v_mul_f32_e32 v38, v60, v60
	v_mul_f32_e32 v39, v62, v62
	v_fmac_f32_e32 v38, v59, v59
	v_fmac_f32_e32 v39, v61, v61
	v_add_f32_e32 v38, v38, v39
	v_mul_f32_e32 v39, v64, v64
	v_mul_f32_e32 v40, v71, v71
	v_fmac_f32_e32 v39, v63, v63
	v_fmac_f32_e32 v40, v65, v65
	v_add_f32_e32 v39, v39, v40
	v_add_f32_e32 v38, v38, v39
	v_lshlrev_b32_e32 v58, 16, v34
	v_and_b32_e32 v41, 0xffff0000, v34
	v_lshlrev_b32_e32 v40, 16, v35
	v_and_b32_e32 v39, 0xffff0000, v35
	v_add_f32_e32 v72, v72, v38
	v_lshlrev_b32_e32 v38, 16, v36
	v_and_b32_e32 v36, 0xffff0000, v36
	v_lshlrev_b32_e32 v35, 16, v37
	v_and_b32_e32 v34, 0xffff0000, v37
	v_add_f32_e32 v37, v58, v41
	v_add_f32_e32 v74, v40, v39
	v_add_f32_e32 v37, v37, v74
	v_add_f32_e32 v74, v38, v36
	v_add_f32_e32 v75, v35, v34
	v_add_f32_e32 v74, v74, v75
	v_add_f32_e32 v37, v37, v74
	v_add_f32_e32 v37, v73, v37
	v_mul_f32_e32 v73, v41, v41
	v_mul_f32_e32 v74, v39, v39
	v_fmac_f32_e32 v73, v58, v58
	v_fmac_f32_e32 v74, v40, v40
	v_add_f32_e32 v73, v73, v74
	v_mul_f32_e32 v74, v36, v36
	v_mul_f32_e32 v75, v34, v34
	v_fmac_f32_e32 v74, v38, v38
	v_fmac_f32_e32 v75, v35, v35
	v_add_f32_e32 v74, v74, v75
	v_add_f32_e32 v73, v73, v74
	v_add_f32_e32 v72, v72, v73
	s_nop 1
	v_mov_b32_dpp v73, v37 quad_perm:[1,0,3,2] row_mask:0xf bank_mask:0xf
	s_cmp_lt_i32 s65, 2
	s_mov_b64 s[10:11], -1
	s_waitcnt lgkmcnt(0)
	v_add_f32_e32 v37, v37, v73
	s_nop 1
	v_mov_b32_dpp v73, v72 quad_perm:[1,0,3,2] row_mask:0xf bank_mask:0xf
	s_waitcnt lgkmcnt(0)
	v_add_f32_e32 v72, v72, v73
	s_nop 1
	v_mov_b32_dpp v73, v37 quad_perm:[2,3,0,1] row_mask:0xf bank_mask:0xf
	s_waitcnt lgkmcnt(0)
	v_add_f32_e32 v37, v37, v73
	s_nop 1
	v_mov_b32_dpp v73, v72 quad_perm:[2,3,0,1] row_mask:0xf bank_mask:0xf
	s_waitcnt lgkmcnt(0)
	v_add_f32_e32 v72, v72, v73
	s_nop 1
	v_mov_b32_dpp v73, v37 row_half_mirror row_mask:0xf bank_mask:0xf
	s_waitcnt lgkmcnt(0)
	v_add_f32_e32 v37, v37, v73
	s_nop 1
	v_mov_b32_dpp v73, v72 row_half_mirror row_mask:0xf bank_mask:0xf
	s_waitcnt lgkmcnt(0)
	v_add_f32_e32 v72, v72, v73
	s_nop 1
	v_mov_b32_dpp v73, v37 row_mirror row_mask:0xf bank_mask:0xf
	s_nop 1
	v_mov_b32_dpp v74, v72 row_mirror row_mask:0xf bank_mask:0xf
	s_cbranch_scc1 .LBB0_1201
	s_cmp_lt_i32 s65, 3
	s_cbranch_scc0 .LBB0_1200
	v_mov_b32_e32 v58, v59
	v_mov_b32_e32 v41, v60
	v_mov_b32_e32 v40, v61
	v_mov_b32_e32 v39, v62
	v_mov_b32_e32 v38, v63
	v_mov_b32_e32 v36, v64
	v_mov_b32_e32 v35, v65
	v_mov_b32_e32 v34, v71

.LBB0_1207:
	s_waitcnt lgkmcnt(1)
	v_add_f32_e32 v37, v37, v73
	v_mul_f32_e32 v43, 0x3b000000, v37
	s_waitcnt lgkmcnt(0)
	v_add_f32_e32 v42, v72, v74
	v_mul_f32_e32 v43, v43, v43
	v_fma_f32 v42, v42, s73, -v43
	v_max_f32_e32 v42, 0, v42
	v_add_f32_e32 v42, 0x358637bd, v42
	v_cmp_gt_f32_e32 vcc, s5, v42
	v_mul_f32_e32 v43, 0x4f800000, v42
	v_fmac_f32_e32 v35, 0xbb000000, v37
	v_cndmask_b32_e32 v42, v42, v43, vcc
	v_sqrt_f32_e32 v43, v42
	v_fmac_f32_e32 v34, 0xbb000000, v37
	v_fmac_f32_e32 v39, 0xbb000000, v37
	v_fmac_f32_e32 v38, 0xbb000000, v37
	v_add_u32_e32 v44, -1, v43
	v_fma_f32 v45, -v44, v43, v42
	v_cmp_ge_f32_e64 s[10:11], 0, v45
	v_add_u32_e32 v45, 1, v43
	v_fmac_f32_e32 v36, 0xbb000000, v37
	v_cndmask_b32_e64 v44, v43, v44, s[10:11]
	v_fma_f32 v43, -v45, v43, v42
	v_cmp_lt_f32_e64 s[10:11], 0, v43
	v_fmac_f32_e32 v58, 0xbb000000, v37
	v_fmac_f32_e32 v41, 0xbb000000, v37
	v_cndmask_b32_e64 v43, v44, v45, s[10:11]
	v_mul_f32_e32 v44, 0x37800000, v43
	v_cndmask_b32_e32 v43, v43, v44, vcc
	v_cmp_class_f32_e32 vcc, v42, v220
	v_fmac_f32_e32 v40, 0xbb000000, v37
	v_lshlrev_b32_e32 v37, 16, v31
	v_cndmask_b32_e32 v42, v43, v42, vcc
	v_div_scale_f32 v43, s[8:9], v42, v42, 1.0
	v_rcp_f32_e32 v44, v43
	v_and_b32_e32 v31, 0xffff0000, v31
	v_and_b32_e32 v48, 0xffff0000, v22
	v_lshlrev_b32_e32 v49, 16, v23
	v_fma_f32 v45, -v43, v44, 1.0
	v_fmac_f32_e32 v44, v45, v44
	v_div_scale_f32 v45, vcc, 1.0, v42, 1.0
	v_mul_f32_e32 v46, v45, v44
	v_fma_f32 v47, -v43, v46, v45
	v_fmac_f32_e32 v46, v47, v44
	v_fma_f32 v43, -v43, v46, v45
	v_div_fmas_f32 v43, v43, v44, v46
	v_div_fixup_f32 v45, v43, v42, 1.0
	v_mul_f32_e32 v35, v45, v35
	v_mul_f32_e32 v34, v45, v34
	v_mul_f32_e32 v39, v45, v39
	v_mul_f32_e32 v38, v45, v38
	v_mul_f32_e32 v36, v45, v36
	v_fma_f32 v35, v2, v35, v6
	v_fma_f32 v34, v3, v34, v7
	v_mul_f32_e32 v42, v45, v58
	v_mul_f32_e32 v41, v45, v41
	v_mul_f32_e32 v40, v45, v40
	v_fma_f32 v39, v11, v39, v15
	v_fma_f32 v38, v0, v38, v4
	v_fma_f32 v36, v1, v36, v5
	v_cvt_pk_bf16_f32 v45, v35, v34
	v_lshlrev_b32_e32 v34, 16, v28
	v_and_b32_e32 v28, 0xffff0000, v28
	v_lshlrev_b32_e32 v35, 16, v29
	v_and_b32_e32 v29, 0xffff0000, v29
	v_fma_f32 v40, v10, v40, v14
	v_cvt_pk_bf16_f32 v43, v40, v39
	v_cvt_pk_bf16_f32 v44, v38, v36
	v_lshlrev_b32_e32 v36, 16, v30
	v_and_b32_e32 v30, 0xffff0000, v30
	v_add_f32_e32 v38, v34, v28
	v_add_f32_e32 v39, v35, v29
	v_add_f32_e32 v38, v38, v39
	v_add_f32_e32 v39, v36, v30
	v_add_f32_e32 v40, v37, v31
	v_fma_f32 v42, v8, v42, v12
	v_add_f32_e32 v39, v39, v40
	v_fma_f32 v41, v9, v41, v13
	v_cvt_pk_bf16_f32 v42, v42, v41
	v_add_f32_e32 v38, v38, v39
	ds_write_b128 v70, v[42:45] offset:2304
	v_add_f32_e32 v42, 0, v38
	v_mul_f32_e32 v38, v28, v28
	v_mul_f32_e32 v39, v29, v29
	v_fmac_f32_e32 v38, v34, v34
	v_fmac_f32_e32 v39, v35, v35
	v_add_f32_e32 v38, v38, v39
	v_mul_f32_e32 v39, v30, v30
	v_mul_f32_e32 v40, v31, v31
	v_fmac_f32_e32 v39, v36, v36
	v_fmac_f32_e32 v40, v37, v37
	v_add_f32_e32 v39, v39, v40
	v_add_f32_e32 v43, v38, v39
	v_lshlrev_b32_e32 v38, 16, v24
	v_and_b32_e32 v24, 0xffff0000, v24
	v_lshlrev_b32_e32 v39, 16, v25
	v_and_b32_e32 v25, 0xffff0000, v25
	v_lshlrev_b32_e32 v40, 16, v26
	v_and_b32_e32 v26, 0xffff0000, v26
	v_lshlrev_b32_e32 v41, 16, v27
	v_and_b32_e32 v27, 0xffff0000, v27
	v_add_f32_e32 v44, v38, v24
	v_add_f32_e32 v45, v39, v25
	v_add_f32_e32 v44, v44, v45
	v_add_f32_e32 v45, v40, v26
	v_add_f32_e32 v46, v41, v27
	v_add_f32_e32 v45, v45, v46
	v_add_f32_e32 v44, v44, v45
	v_add_f32_e32 v51, v42, v44
	v_mul_f32_e32 v42, v24, v24
	v_mul_f32_e32 v44, v25, v25
	v_fmac_f32_e32 v42, v38, v38
	v_fmac_f32_e32 v44, v39, v39
	v_add_f32_e32 v42, v42, v44
	v_mul_f32_e32 v44, v26, v26
	v_mul_f32_e32 v45, v27, v27
	v_fmac_f32_e32 v44, v40, v40
	v_fmac_f32_e32 v45, v41, v41
	v_add_f32_e32 v44, v44, v45
	v_add_f32_e32 v42, v42, v44
	v_add_f32_e32 v43, v43, v42
	v_lshlrev_b32_e32 v42, 16, v20
	v_and_b32_e32 v44, 0xffff0000, v20
	v_lshlrev_b32_e32 v45, 16, v21
	v_and_b32_e32 v46, 0xffff0000, v21
	v_lshlrev_b32_e32 v47, 16, v22
	v_and_b32_e32 v50, 0xffff0000, v23
	v_add_f32_e32 v20, v42, v44
	v_add_f32_e32 v21, v45, v46
	v_add_f32_e32 v20, v20, v21
	v_add_f32_e32 v21, v47, v48
	v_add_f32_e32 v22, v49, v50
	v_add_f32_e32 v21, v21, v22
	v_add_f32_e32 v20, v20, v21
	v_add_f32_e32 v51, v51, v20
	v_mul_f32_e32 v20, v44, v44
	v_mul_f32_e32 v21, v46, v46
	v_fmac_f32_e32 v20, v42, v42
	v_fmac_f32_e32 v21, v45, v45
	v_add_f32_e32 v20, v20, v21
	v_mul_f32_e32 v21, v48, v48
	v_mul_f32_e32 v22, v50, v50
	v_fmac_f32_e32 v21, v47, v47
	v_fmac_f32_e32 v22, v49, v49
	v_add_f32_e32 v21, v21, v22
	v_add_f32_e32 v20, v20, v21
	v_add_f32_e32 v52, v43, v20
	v_lshlrev_b32_e32 v43, 16, v16
	v_and_b32_e32 v23, 0xffff0000, v16
	v_lshlrev_b32_e32 v22, 16, v17
	v_and_b32_e32 v21, 0xffff0000, v17
	v_lshlrev_b32_e32 v20, 16, v18
	v_and_b32_e32 v18, 0xffff0000, v18
	v_lshlrev_b32_e32 v17, 16, v19
	v_and_b32_e32 v16, 0xffff0000, v19
	v_add_f32_e32 v19, v43, v23
	v_add_f32_e32 v53, v22, v21
	v_add_f32_e32 v19, v19, v53
	v_add_f32_e32 v53, v20, v18
	v_add_f32_e32 v54, v17, v16
	v_add_f32_e32 v53, v53, v54
	v_add_f32_e32 v19, v19, v53
	v_add_f32_e32 v19, v51, v19
	v_mul_f32_e32 v51, v23, v23
	v_mul_f32_e32 v53, v21, v21
	v_fmac_f32_e32 v51, v43, v43
	v_fmac_f32_e32 v53, v22, v22
	v_add_f32_e32 v51, v51, v53
	v_mul_f32_e32 v53, v18, v18
	v_mul_f32_e32 v54, v16, v16
	v_fmac_f32_e32 v53, v20, v20
	v_fmac_f32_e32 v54, v17, v17
	v_add_f32_e32 v53, v53, v54
	v_add_f32_e32 v51, v51, v53
	v_add_f32_e32 v51, v52, v51
	s_nop 1
	v_mov_b32_dpp v52, v19 quad_perm:[1,0,3,2] row_mask:0xf bank_mask:0xf
	s_cmp_lt_i32 s65, 2
	s_mov_b64 s[10:11], -1
	s_waitcnt lgkmcnt(0)
	v_add_f32_e32 v19, v19, v52
	s_nop 1
	v_mov_b32_dpp v52, v51 quad_perm:[1,0,3,2] row_mask:0xf bank_mask:0xf
	s_waitcnt lgkmcnt(0)
	v_add_f32_e32 v51, v51, v52
	s_nop 1
	v_mov_b32_dpp v52, v19 quad_perm:[2,3,0,1] row_mask:0xf bank_mask:0xf
	s_waitcnt lgkmcnt(0)
	v_add_f32_e32 v19, v19, v52
	s_nop 1
	v_mov_b32_dpp v52, v51 quad_perm:[2,3,0,1] row_mask:0xf bank_mask:0xf
	s_waitcnt lgkmcnt(0)
	v_add_f32_e32 v51, v51, v52
	s_nop 1
	v_mov_b32_dpp v52, v19 row_half_mirror row_mask:0xf bank_mask:0xf
	s_waitcnt lgkmcnt(0)
	v_add_f32_e32 v19, v19, v52
	s_nop 1
	v_mov_b32_dpp v52, v51 row_half_mirror row_mask:0xf bank_mask:0xf
	s_waitcnt lgkmcnt(0)
	v_add_f32_e32 v51, v51, v52
	s_nop 1
	v_mov_b32_dpp v52, v19 row_mirror row_mask:0xf bank_mask:0xf
	s_nop 1
	v_mov_b32_dpp v32, v51 row_mirror row_mask:0xf bank_mask:0xf
	s_cbranch_scc1 .LBB0_1211
	s_cmp_lt_i32 s65, 3
	s_cbranch_scc0 .LBB0_1210
	v_mov_b32_e32 v43, v42
	v_mov_b32_e32 v23, v44
	v_mov_b32_e32 v22, v45
	v_mov_b32_e32 v21, v46
	v_mov_b32_e32 v20, v47
	v_mov_b32_e32 v18, v48
	v_mov_b32_e32 v17, v49
	v_mov_b32_e32 v16, v50
